# v111 + GEMM epilogue priority flip: waves 4-7 drop to 0, waves 0-3 raised to 1 for the convert/store tail (all reset at the pull barrier)
# baseline (speedup 1.0000x reference)
.LBB0_148:
	s_setprio 0
	v_readfirstlane_b32 s99, v195
	s_cmpk_lt_u32 s99, 0x100
	s_cbranch_scc0 .Lepf_0
	s_setprio 1
